# GEMM tile->block remap so that blocks b and b+8 (same XCD) take adjacent N-tiles of the same M-tile (ph0, ph7, ph5)
# speedup vs baseline: 1.0058x; 1.0048x over previous
;     ...
;   int bid0 = (int)(blockIdx.x + zz) + rot; if (bid0 >= (int)gridDim.x) bid0 -= (int)gridDim.x;
;   for (int t = bid0; t < mtiles * ntiles; t += (gridDim.x + zz)) {
;     int mt = t / ntiles, nt = t % ntiles;
;     int m0 = mt * 128, n0 = nt * 128;
;     gemm_tile<(EPI == EPI_OUT) ? 1 : 0>(A + (size_t)m0 * lda, lda, Bt + (size_t)n0 * ldb, ldb, K, smem, (const float*)(p.ws + zz + O_SSQ) + (size_t)m0 * 4);
.LBB0_775:
	s_mov_b32 s0, 0
	s_lshr_b32 s10, s34, 3
	s_mov_b32 s18, 0
	s_add_i32 s1, s18, s87
	s_cmp_ge_i32 s1, s90
	s_cselect_b32 s2, s90, 0
	s_sub_i32 s11, s1, s2
	s_lshr_b32 s1, s11, 4
	s_lshl_b32 s1, s1, 3
	s_and_b32 s2, s11, 7
	s_or_b32 s1, s1, s2
	s_lshl_b32 s1, s1, 1
	s_bfe_u32 s2, s11, 0x10003
	s_or_b32 s11, s1, s2
	s_cmp_ge_i32 s11, s10
	s_cbranch_scc1 .LBB0_785
	s_ashr_i32 s1, s0, 31
	s_add_u32 s0, s88, s0
	s_addc_u32 s1, s89, s1
	s_load_dwordx2 s[0:1], s[0:1], 0x118
	v_add_u32_e32 v120, s18, v128
	s_movk_i32 s2, 0x1000
	v_cmp_gt_i32_e64 s[4:5], s2, v120
	v_lshlrev_b32_e32 v121, 2, v120
	s_waitcnt lgkmcnt(0)
	s_add_u32 s12, s0, 0x10b19000
	s_addc_u32 s13, s1, 0
	s_lshl_b32 s2, s94, 22
	s_add_u32 s2, s0, s2
	s_addc_u32 s3, s1, 0
	s_add_u32 s14, s2, 0x3299000
	s_addc_u32 s15, s3, 0
	s_add_u32 s16, s0, 0x15319000
	s_addc_u32 s17, s1, 0
	s_add_i32 s18, s18, s90
	s_add_u32 s19, s0, 0x10b19080
	s_addc_u32 s20, s1, 0
	s_add_u32 s21, s2, 0x3299080
	s_addc_u32 s22, s3, 0
	s_branch .LBB0_778

;     ...
;   int bid0 = (int)(blockIdx.x + zz) + rot; if (bid0 >= (int)gridDim.x) bid0 -= (int)gridDim.x;
;   for (int t = bid0; t < mtiles * ntiles; t += (gridDim.x + zz)) {
;     int mt = t / ntiles, nt = t % ntiles;
;     int m0 = mt * 128, n0 = nt * 128;
;     gemm_tile<(EPI == EPI_OUT) ? 1 : 0>(A + (size_t)m0 * lda, lda, Bt + (size_t)n0 * ldb, ldb, K, smem, (const float*)(p.ws + zz + O_SSQ) + (size_t)m0 * 4);
.LBB0_801:
	s_andn2_b64 vcc, exec, s[0:1]
	s_cbranch_vccnz .LBB0_815
	s_mov_b32 s0, 0
	s_lshr_b32 s18, s34, 4
	s_mov_b32 s29, 0
	s_add_i32 s1, s29, s87
	s_cmp_ge_i32 s1, s90
	s_cselect_b32 s2, s90, 0
	s_sub_i32 s19, s1, s2
	s_lshr_b32 s1, s19, 4
	s_lshl_b32 s1, s1, 3
	s_and_b32 s2, s19, 7
	s_or_b32 s1, s1, s2
	s_lshl_b32 s1, s1, 1
	s_bfe_u32 s2, s19, 0x10003
	s_or_b32 s19, s1, s2
	s_cmp_ge_i32 s19, s18
	s_cbranch_scc1 .LBB0_815
	s_ashr_i32 s1, s0, 31
	s_add_u32 s0, s88, s0
	s_addc_u32 s1, s89, s1
	s_load_dwordx2 s[0:1], s[0:1], 0x118
	v_add_u32_e32 v129, s29, v128
	s_movk_i32 s2, 0x1000
	v_cmp_gt_i32_e64 s[4:5], s2, v129
	s_mul_i32 s28, s94, 9
	s_waitcnt lgkmcnt(0)
	s_add_u32 s20, s0, 0x12f19000
	s_addc_u32 s21, s1, 0
	s_lshl_b32 s2, s94, 21
	s_add_u32 s6, s0, s2
	s_addc_u32 s7, s1, 0
	s_add_u32 s22, s6, 0x1a59000
	s_addc_u32 s23, s7, 0
	s_ashr_i32 s3, s29, 31
	s_add_u32 s2, s0, s29
	s_addc_u32 s3, s1, s3
	s_add_u32 s24, s2, 0x2dd25800
	s_addc_u32 s25, s3, 0
	s_add_u32 s26, s2, 0xc319000
	s_addc_u32 s27, s3, 0
	s_add_i32 s29, s29, s90
	s_add_u32 s34, s0, 0x12f19080
	s_addc_u32 s35, s1, 0
	s_add_u32 s36, s6, 0x1a59080
	s_addc_u32 s37, s7, 0
	v_lshlrev_b32_e32 v131, 2, v129
	s_branch .LBB0_805

;     ...
;   int bid0 = (int)(blockIdx.x + zz) + rot; if (bid0 >= (int)gridDim.x) bid0 -= (int)gridDim.x;
;   for (int t = bid0; t < mtiles * ntiles; t += (gridDim.x + zz)) {
;     int mt = t / ntiles, nt = t % ntiles;
;     int m0 = mt * 128, n0 = nt * 128;
;     gemm_tile<(EPI == EPI_OUT) ? 1 : 0>(A + (size_t)m0 * lda, lda, Bt + (size_t)n0 * ldb, ldb, K, smem, (const float*)(p.ws + zz + O_SSQ) + (size_t)m0 * 4);
.LBB0_1453:
	s_andn2_b64 vcc, exec, s[2:3]
	s_cbranch_vccnz .LBB0_1510
	v_readlane_b32 s2, v254, 22
	s_cmp_gt_i32 s2, -1
	s_mov_b64 s[2:3], -1
	s_cbranch_scc0 .LBB0_1466
	s_mov_b32 s0, 0
	s_mov_b32 s17, 0
	s_add_i32 s1, s17, s87
	s_cmp_ge_i32 s1, s90
	s_cselect_b32 s2, s90, 0
	s_sub_i32 s10, s1, s2
	s_lshr_b32 s1, s10, 4
	s_lshl_b32 s1, s1, 3
	s_and_b32 s2, s10, 7
	s_or_b32 s1, s1, s2
	s_lshl_b32 s1, s1, 1
	s_bfe_u32 s2, s10, 0x10003
	s_or_b32 s10, s1, s2
	s_cmpk_gt_i32 s10, 0xd7f
	s_cbranch_scc1 .LBB0_1465
	s_ashr_i32 s1, s0, 31
	s_add_u32 s0, s88, s0
	s_addc_u32 s1, s89, s1
	s_load_dwordx2 s[0:1], s[0:1], 0x118
	s_mul_i32 s2, s94, 0x600000
	v_add_u32_e32 v120, s17, v128
	s_movk_i32 s3, 0x1000
	v_cmp_gt_i32_e64 s[4:5], s3, v120
	s_waitcnt lgkmcnt(0)
	s_add_u32 s11, s0, 0x10b19000
	s_addc_u32 s12, s1, 0
	s_add_u32 s2, s0, s2
	s_addc_u32 s3, s1, 0
	s_add_u32 s13, s2, 0x119000
	s_addc_u32 s14, s3, 0
	s_add_u32 s15, s0, 0x15319000
	s_addc_u32 s16, s1, 0
	s_add_i32 s17, s17, s90
	s_add_u32 s18, s0, 0x10b19080
	s_addc_u32 s19, s1, 0
	s_add_u32 s20, s2, 0x119080
	s_addc_u32 s21, s3, 0
	v_lshlrev_b32_e32 v121, 2, v120
	s_branch .LBB0_1458
